# hand-written VALU-counting radix select for the top-k mask (replaces hipcc's SALU ballot/bcnt loop), nop-free mask transpose
# speedup vs baseline: 1.0145x; 1.0145x over previous
.LBB0_592:
	s_lshl_b64 s[8:9], s[8:9], 13
	s_add_u32 s8, s18, s8
	s_addc_u32 s9, s19, s9
	global_load_dword v69, v32, s[8:9]
	global_load_dword v68, v32, s[8:9] offset:256
	global_load_dword v67, v32, s[8:9] offset:512
	global_load_dword v65, v32, s[8:9] offset:768
	global_load_dword v64, v32, s[8:9] offset:1024
	global_load_dword v3, v5, s[8:9]
	global_load_dword v38, v6, s[8:9]
	global_load_dword v39, v7, s[8:9]
	global_load_dword v40, v8, s[8:9]
	global_load_dword v41, v9, s[8:9]
	global_load_dword v42, v10, s[8:9]
	global_load_dword v43, v11, s[8:9]
	global_load_dword v44, v12, s[8:9]
	global_load_dword v45, v13, s[8:9]
	global_load_dword v46, v14, s[8:9]
	global_load_dword v47, v15, s[8:9]
	global_load_dword v48, v16, s[8:9]
	global_load_dword v49, v17, s[8:9]
	global_load_dword v50, v18, s[8:9]
	global_load_dword v51, v19, s[8:9]
	global_load_dword v52, v20, s[8:9]
	global_load_dword v53, v21, s[8:9]
	global_load_dword v54, v22, s[8:9]
	global_load_dword v61, v23, s[8:9]
	global_load_dword v62, v24, s[8:9]
	global_load_dword v63, v25, s[8:9]
	global_load_dword v76, v26, s[8:9]
	global_load_dword v77, v27, s[8:9]
	global_load_dword v78, v28, s[8:9]
	global_load_dword v79, v29, s[8:9]
	global_load_dword v80, v30, s[8:9]
	global_load_dword v81, v31, s[8:9]
	s_mov_b32 s15, 31
	s_mov_b32 s2, 0
	s_mov_b64 s[42:43], 0
	s_mov_b32 s47, 0
	s_waitcnt vmcnt(31)
	v_ashrrev_i32_e32 v2, 31, v69
	s_waitcnt vmcnt(30)
	v_ashrrev_i32_e32 v33, 31, v68
	v_or_b32_e32 v72, 0x80000000, v33
	v_bitop3_b32 v36, v33, v68, s33 bitop3:0x36
	s_waitcnt vmcnt(29)
	v_ashrrev_i32_e32 v33, 31, v67
	s_waitcnt vmcnt(26)
	v_ashrrev_i32_e32 v37, 31, v3
	v_bitop3_b32 v3, v37, v3, s33 bitop3:0x36
	v_cndmask_b32_e64 v37, v3, 0, s[24:25]
	s_waitcnt vmcnt(25)
	v_ashrrev_i32_e32 v3, 31, v38
	v_bitop3_b32 v3, v3, v38, s33 bitop3:0x36
	v_cndmask_b32_e64 v38, v3, 0, s[26:27]
	s_waitcnt vmcnt(24)
	v_ashrrev_i32_e32 v3, 31, v39
	v_bitop3_b32 v3, v3, v39, s33 bitop3:0x36
	v_cndmask_b32_e64 v39, v3, 0, s[28:29]
	s_waitcnt vmcnt(23)
	v_ashrrev_i32_e32 v3, 31, v40
	v_bitop3_b32 v3, v3, v40, s33 bitop3:0x36
	s_waitcnt vmcnt(22)
	v_ashrrev_i32_e32 v40, 31, v41
	v_bitop3_b32 v40, v40, v41, s33 bitop3:0x36
	s_waitcnt vmcnt(21)
	v_ashrrev_i32_e32 v41, 31, v42
	v_bitop3_b32 v41, v41, v42, s33 bitop3:0x36
	s_waitcnt vmcnt(20)
	v_ashrrev_i32_e32 v42, 31, v43
	v_bitop3_b32 v42, v42, v43, s33 bitop3:0x36
	s_waitcnt vmcnt(19)
	v_ashrrev_i32_e32 v43, 31, v44
	v_bitop3_b32 v43, v43, v44, s33 bitop3:0x36
	s_waitcnt vmcnt(18)
	v_ashrrev_i32_e32 v44, 31, v45
	v_bitop3_b32 v44, v44, v45, s33 bitop3:0x36
	s_waitcnt vmcnt(17)
	v_ashrrev_i32_e32 v45, 31, v46
	v_bitop3_b32 v45, v45, v46, s33 bitop3:0x36
	s_waitcnt vmcnt(16)
	v_ashrrev_i32_e32 v46, 31, v47
	v_bitop3_b32 v46, v46, v47, s33 bitop3:0x36
	s_waitcnt vmcnt(15)
	v_ashrrev_i32_e32 v47, 31, v48
	v_bitop3_b32 v66, v47, v48, s33 bitop3:0x36
	s_waitcnt vmcnt(14)
	v_ashrrev_i32_e32 v47, 31, v49
	v_bitop3_b32 v47, v47, v49, s33 bitop3:0x36
	v_cndmask_b32_e64 v60, v47, 0, s[68:69]
	s_waitcnt vmcnt(13)
	v_ashrrev_i32_e32 v47, 31, v50
	v_bitop3_b32 v47, v47, v50, s33 bitop3:0x36
	v_cndmask_b32_e64 v59, v47, 0, s[70:71]
	s_waitcnt vmcnt(12)
	v_ashrrev_i32_e32 v47, 31, v51
	v_bitop3_b32 v47, v47, v51, s33 bitop3:0x36
	v_cndmask_b32_e64 v58, v47, 0, s[72:73]
	s_waitcnt vmcnt(11)
	v_ashrrev_i32_e32 v47, 31, v52
	v_bitop3_b32 v47, v47, v52, s33 bitop3:0x36
	v_cndmask_b32_e64 v57, v47, 0, s[74:75]
	s_waitcnt vmcnt(10)
	v_ashrrev_i32_e32 v47, 31, v53
	v_bitop3_b32 v47, v47, v53, s33 bitop3:0x36
	v_cndmask_b32_e64 v56, v47, 0, s[76:77]
	s_waitcnt vmcnt(9)
	v_ashrrev_i32_e32 v47, 31, v54
	v_bitop3_b32 v47, v47, v54, s33 bitop3:0x36
	v_cndmask_b32_e64 v55, v47, 0, s[78:79]
	s_waitcnt vmcnt(8)
	v_ashrrev_i32_e32 v47, 31, v61
	v_bitop3_b32 v47, v47, v61, s33 bitop3:0x36
	v_cndmask_b32_e64 v54, v47, 0, s[80:81]
	s_waitcnt vmcnt(7)
	v_ashrrev_i32_e32 v47, 31, v62
	v_bitop3_b32 v70, v47, v62, s33 bitop3:0x36
	s_waitcnt vmcnt(6)
	v_ashrrev_i32_e32 v47, 31, v63
	v_bitop3_b32 v47, v47, v63, s33 bitop3:0x36
	v_cndmask_b32_e64 v53, v47, 0, s[86:87]
	s_waitcnt vmcnt(5)
	v_ashrrev_i32_e32 v47, 31, v76
	v_bitop3_b32 v47, v47, v76, s33 bitop3:0x36
	v_cndmask_b32_e64 v52, v47, 0, s[88:89]
	s_waitcnt vmcnt(4)
	v_ashrrev_i32_e32 v47, 31, v77
	v_bitop3_b32 v47, v47, v77, s33 bitop3:0x36
	v_cndmask_b32_e64 v51, v47, 0, s[90:91]
	s_waitcnt vmcnt(3)
	v_ashrrev_i32_e32 v47, 31, v78
	v_bitop3_b32 v47, v47, v78, s33 bitop3:0x36
	v_cndmask_b32_e64 v50, v47, 0, s[92:93]
	s_waitcnt vmcnt(2)
	v_ashrrev_i32_e32 v47, 31, v79
	v_bitop3_b32 v47, v47, v79, s33 bitop3:0x36
	v_cndmask_b32_e64 v49, v47, 0, s[94:95]
	s_waitcnt vmcnt(1)
	v_ashrrev_i32_e32 v47, 31, v80
	v_bitop3_b32 v47, v47, v80, s33 bitop3:0x36
	v_or_b32_e32 v73, 0x80000000, v33
	v_bitop3_b32 v35, v33, v67, s33 bitop3:0x36
	v_ashrrev_i32_e32 v33, 31, v65
	v_cndmask_b32_e64 v48, v47, 0, s[96:97]
	s_waitcnt vmcnt(0)
	v_ashrrev_i32_e32 v47, 31, v81
	v_or_b32_e32 v74, 0x80000000, v33
	v_bitop3_b32 v34, v33, v65, s33 bitop3:0x36
	v_ashrrev_i32_e32 v33, 31, v64
	v_bitop3_b32 v47, v47, v81, s33 bitop3:0x36
	v_or_b32_e32 v71, 0x80000000, v2
	v_bitop3_b32 v2, v2, v69, s33 bitop3:0x36
	v_or_b32_e32 v75, 0x80000000, v33
	v_bitop3_b32 v33, v33, v64, s33 bitop3:0x36
	v_cndmask_b32_e64 v40, v40, 0, s[50:51]
	v_cndmask_b32_e64 v41, v41, 0, s[52:53]
	v_cndmask_b32_e64 v42, v42, 0, s[54:55]
	v_cndmask_b32_e64 v43, v43, 0, s[56:57]
	v_cndmask_b32_e64 v44, v44, 0, s[58:59]
	v_cndmask_b32_e64 v45, v45, 0, s[60:61]
	v_cndmask_b32_e64 v46, v46, 0, s[62:63]
	v_cndmask_b32_e64 v47, 0, v47, s[6:7]
	v_cndmask_b32_e64 v63, v3, 0, s[30:31]
	v_cndmask_b32_e64 v62, v66, 0, s[64:65]
	v_cndmask_b32_e64 v61, v70, 0, s[82:83]
	s_mov_b32 s40, 1
	s_cmp_lg_u64 s[48:49], 0
	s_addc_u32 s40, s40, 0
	s_cmp_lg_u64 s[66:67], 0
	s_addc_u32 s40, s40, 0
	s_cmp_lg_u64 s[84:85], 0
	s_addc_u32 s40, s40, 0
	s_mov_b32 s2, 0
	s_mov_b32 s15, 31
.Lmy_tk_pass:
	s_lshl_b32 s8, 1, s15
	s_or_b32 s35, s8, s2
	v_mov_b32_e32 v77, 0
	v_mov_b32_e32 v78, 0
	v_cmp_le_u32_e32 vcc, s35, v2
	v_cmp_le_u32_e64 s[98:99], s35, v36
	v_cmp_le_u32_e64 s[100:101], s35, v35
	v_addc_co_u32_e32 v77, vcc, 0, v77, vcc
	v_cmp_le_u32_e32 vcc, s35, v34
	v_addc_co_u32_e64 v78, s[98:99], 0, v78, s[98:99]
	v_cmp_le_u32_e64 s[98:99], s35, v33
	v_addc_co_u32_e64 v77, s[100:101], 0, v77, s[100:101]
	v_cmp_le_u32_e64 s[100:101], s35, v37
	v_addc_co_u32_e32 v78, vcc, 0, v78, vcc
	v_cmp_le_u32_e32 vcc, s35, v38
	v_addc_co_u32_e64 v77, s[98:99], 0, v77, s[98:99]
	v_cmp_le_u32_e64 s[98:99], s35, v39
	v_addc_co_u32_e64 v78, s[100:101], 0, v78, s[100:101]
	v_addc_co_u32_e32 v77, vcc, 0, v77, vcc
	v_addc_co_u32_e64 v78, s[98:99], 0, v78, s[98:99]
	s_cmp_lt_u32 s40, 2
	s_cbranch_scc1 .Lmy_tk_red
	v_cmp_le_u32_e32 vcc, s35, v63
	v_cmp_le_u32_e64 s[98:99], s35, v40
	v_cmp_le_u32_e64 s[100:101], s35, v41
	v_addc_co_u32_e32 v77, vcc, 0, v77, vcc
	v_cmp_le_u32_e32 vcc, s35, v42
	v_addc_co_u32_e64 v78, s[98:99], 0, v78, s[98:99]
	v_cmp_le_u32_e64 s[98:99], s35, v43
	v_addc_co_u32_e64 v77, s[100:101], 0, v77, s[100:101]
	v_cmp_le_u32_e64 s[100:101], s35, v44
	v_addc_co_u32_e32 v78, vcc, 0, v78, vcc
	v_cmp_le_u32_e32 vcc, s35, v45
	v_addc_co_u32_e64 v77, s[98:99], 0, v77, s[98:99]
	v_cmp_le_u32_e64 s[98:99], s35, v46
	v_addc_co_u32_e64 v78, s[100:101], 0, v78, s[100:101]
	v_addc_co_u32_e32 v77, vcc, 0, v77, vcc
	v_addc_co_u32_e64 v78, s[98:99], 0, v78, s[98:99]
	s_cmp_lt_u32 s40, 3
	s_cbranch_scc1 .Lmy_tk_red
	v_cmp_le_u32_e32 vcc, s35, v62
	v_cmp_le_u32_e64 s[98:99], s35, v60
	v_cmp_le_u32_e64 s[100:101], s35, v59
	v_addc_co_u32_e32 v77, vcc, 0, v77, vcc
	v_cmp_le_u32_e32 vcc, s35, v58
	v_addc_co_u32_e64 v78, s[98:99], 0, v78, s[98:99]
	v_cmp_le_u32_e64 s[98:99], s35, v57
	v_addc_co_u32_e64 v77, s[100:101], 0, v77, s[100:101]
	v_cmp_le_u32_e64 s[100:101], s35, v56
	v_addc_co_u32_e32 v78, vcc, 0, v78, vcc
	v_cmp_le_u32_e32 vcc, s35, v55
	v_addc_co_u32_e64 v77, s[98:99], 0, v77, s[98:99]
	v_cmp_le_u32_e64 s[98:99], s35, v54
	v_addc_co_u32_e64 v78, s[100:101], 0, v78, s[100:101]
	v_addc_co_u32_e32 v77, vcc, 0, v77, vcc
	v_addc_co_u32_e64 v78, s[98:99], 0, v78, s[98:99]
	s_cmp_lt_u32 s40, 4
	s_cbranch_scc1 .Lmy_tk_red
	v_cmp_le_u32_e32 vcc, s35, v61
	v_cmp_le_u32_e64 s[98:99], s35, v53
	v_cmp_le_u32_e64 s[100:101], s35, v52
	v_addc_co_u32_e32 v77, vcc, 0, v77, vcc
	v_cmp_le_u32_e32 vcc, s35, v51
	v_addc_co_u32_e64 v78, s[98:99], 0, v78, s[98:99]
	v_cmp_le_u32_e64 s[98:99], s35, v50
	v_addc_co_u32_e64 v77, s[100:101], 0, v77, s[100:101]
	v_cmp_le_u32_e64 s[100:101], s35, v49
	v_addc_co_u32_e32 v78, vcc, 0, v78, vcc
	v_cmp_le_u32_e32 vcc, s35, v48
	v_addc_co_u32_e64 v77, s[98:99], 0, v77, s[98:99]
	v_cmp_le_u32_e64 s[98:99], s35, v47
	v_addc_co_u32_e64 v78, s[100:101], 0, v78, s[100:101]
	v_addc_co_u32_e32 v77, vcc, 0, v77, vcc
	v_addc_co_u32_e64 v78, s[98:99], 0, v78, s[98:99]
.Lmy_tk_red:
	v_add_u32_e32 v77, v77, v78
	s_nop 1
	v_add_u32_dpp v77, v77, v77 row_shr:1 row_mask:0xf bank_mask:0xf
	s_nop 1
	v_add_u32_dpp v77, v77, v77 row_shr:2 row_mask:0xf bank_mask:0xf
	s_nop 1
	v_add_u32_dpp v77, v77, v77 row_shr:4 row_mask:0xf bank_mask:0xf
	s_nop 1
	v_add_u32_dpp v77, v77, v77 row_shr:8 row_mask:0xf bank_mask:0xf
	s_nop 1
	v_add_u32_dpp v77, v77, v77 row_bcast:15 row_mask:0xa bank_mask:0xf
	s_nop 1
	v_add_u32_dpp v77, v77, v77 row_bcast:31 row_mask:0xc bank_mask:0xf
	s_nop 1
	v_readlane_b32 s46, v77, 63
	s_cmpk_lt_u32 s46, 0x100
	s_cbranch_scc1 .Lmy_tk_next
	s_mov_b32 s2, s35
	s_cmpk_eq_u32 s46, 0x100
	s_cbranch_scc1 .Lmy_tk_done
.Lmy_tk_next:
	s_add_i32 s15, s15, -1
	s_cmp_ge_i32 s15, 0
	s_cbranch_scc1 .Lmy_tk_pass
.Lmy_tk_done:
	v_mov_b32_e32 v78, 0
	v_mov_b32_e32 v79, 0
	v_cmp_le_u32_e32 vcc, s2, v2
	v_cmp_le_u32_e64 s[98:99], s2, v36
	v_cmp_le_u32_e64 s[100:101], s2, v35
	v_writelane_b32 v78, vcc_lo, 0
	v_writelane_b32 v79, vcc_hi, 0
	v_cmp_le_u32_e32 vcc, s2, v34
	v_writelane_b32 v78, s98, 1
	v_writelane_b32 v79, s99, 1
	v_cmp_le_u32_e64 s[98:99], s2, v33
	v_writelane_b32 v78, s100, 2
	v_writelane_b32 v79, s101, 2
	v_cmp_le_u32_e64 s[100:101], s2, v37
	v_writelane_b32 v78, vcc_lo, 3
	v_writelane_b32 v79, vcc_hi, 3
	v_cmp_le_u32_e32 vcc, s2, v38
	v_writelane_b32 v78, s98, 4
	v_writelane_b32 v79, s99, 4
	v_cmp_le_u32_e64 s[98:99], s2, v39
	v_writelane_b32 v78, s100, 5
	v_writelane_b32 v79, s101, 5
	v_cmp_le_u32_e64 s[100:101], s2, v63
	v_writelane_b32 v78, vcc_lo, 6
	v_writelane_b32 v79, vcc_hi, 6
	v_cmp_le_u32_e32 vcc, s2, v40
	v_writelane_b32 v78, s98, 7
	v_writelane_b32 v79, s99, 7
	v_cmp_le_u32_e64 s[98:99], s2, v41
	v_writelane_b32 v78, s100, 8
	v_writelane_b32 v79, s101, 8
	v_cmp_le_u32_e64 s[100:101], s2, v42
	v_writelane_b32 v78, vcc_lo, 9
	v_writelane_b32 v79, vcc_hi, 9
	v_cmp_le_u32_e32 vcc, s2, v43
	v_writelane_b32 v78, s98, 10
	v_writelane_b32 v79, s99, 10
	v_cmp_le_u32_e64 s[98:99], s2, v44
	v_writelane_b32 v78, s100, 11
	v_writelane_b32 v79, s101, 11
	v_cmp_le_u32_e64 s[100:101], s2, v45
	v_writelane_b32 v78, vcc_lo, 12
	v_writelane_b32 v79, vcc_hi, 12
	v_cmp_le_u32_e32 vcc, s2, v46
	v_writelane_b32 v78, s98, 13
	v_writelane_b32 v79, s99, 13
	v_cmp_le_u32_e64 s[98:99], s2, v62
	v_writelane_b32 v78, s100, 14
	v_writelane_b32 v79, s101, 14
	v_cmp_le_u32_e64 s[100:101], s2, v60
	v_writelane_b32 v78, vcc_lo, 15
	v_writelane_b32 v79, vcc_hi, 15
	v_cmp_le_u32_e32 vcc, s2, v59
	v_writelane_b32 v78, s98, 16
	v_writelane_b32 v79, s99, 16
	v_cmp_le_u32_e64 s[98:99], s2, v58
	v_writelane_b32 v78, s100, 17
	v_writelane_b32 v79, s101, 17
	v_cmp_le_u32_e64 s[100:101], s2, v57
	v_writelane_b32 v78, vcc_lo, 18
	v_writelane_b32 v79, vcc_hi, 18
	v_cmp_le_u32_e32 vcc, s2, v56
	v_writelane_b32 v78, s98, 19
	v_writelane_b32 v79, s99, 19
	v_cmp_le_u32_e64 s[98:99], s2, v55
	v_writelane_b32 v78, s100, 20
	v_writelane_b32 v79, s101, 20
	v_cmp_le_u32_e64 s[100:101], s2, v54
	v_writelane_b32 v78, vcc_lo, 21
	v_writelane_b32 v79, vcc_hi, 21
	v_cmp_le_u32_e32 vcc, s2, v61
	v_writelane_b32 v78, s98, 22
	v_writelane_b32 v79, s99, 22
	v_cmp_le_u32_e64 s[98:99], s2, v53
	v_writelane_b32 v78, s100, 23
	v_writelane_b32 v79, s101, 23
	v_cmp_le_u32_e64 s[100:101], s2, v52
	v_writelane_b32 v78, vcc_lo, 24
	v_writelane_b32 v79, vcc_hi, 24
	v_cmp_le_u32_e32 vcc, s2, v51
	v_writelane_b32 v78, s98, 25
	v_writelane_b32 v79, s99, 25
	v_cmp_le_u32_e64 s[98:99], s2, v50
	v_writelane_b32 v78, s100, 26
	v_writelane_b32 v79, s101, 26
	v_cmp_le_u32_e64 s[100:101], s2, v49
	v_writelane_b32 v78, vcc_lo, 27
	v_writelane_b32 v79, vcc_hi, 27
	v_cmp_le_u32_e32 vcc, s2, v48
	v_writelane_b32 v78, s98, 28
	v_writelane_b32 v79, s99, 28
	v_cmp_le_u32_e64 s[98:99], s2, v47
	v_writelane_b32 v78, s100, 29
	v_writelane_b32 v79, s101, 29
	v_writelane_b32 v78, vcc_lo, 30
	v_writelane_b32 v79, vcc_hi, 30
	v_writelane_b32 v78, s98, 31
	v_writelane_b32 v79, s99, 31
	s_and_saveexec_b64 s[8:9], s[4:5]
	s_cbranch_execz .LBB0_714
	global_store_dwordx2 v163, v[78:79], s[44:45]

.LBB0_715:
	global_store_dword v32, v4, s[44:45]
	s_branch .LBB0_589
.LBB0_718:
	v_readlane_b32 s0, v255, 19
	v_readlane_b32 s1, v255, 20
	s_load_dwordx2 s[8:9], s[0:1], 0xc0
	v_lshlrev_b32_e32 v146, 6, v154
	v_mov_b32_e32 v147, 0
	s_mov_b64 s[4:5], 0x2c000000
	s_load_dwordx2 s[2:3], s[0:1], 0x50
	s_load_dwordx2 s[6:7], s[0:1], 0x60
	s_waitcnt lgkmcnt(0)
	v_lshl_add_u64 v[4:5], s[8:9], 0, v[146:147]
	v_lshl_add_u64 v[148:149], v[4:5], 0, s[4:5]
	v_mbcnt_lo_u32_b32 v4, -1, 0
	v_mbcnt_hi_u32_b32 v4, -1, v4
	v_and_b32_e32 v6, 64, v4
	v_xor_b32_e32 v5, 1, v4
	v_add_u32_e32 v6, 64, v6
	v_cmp_lt_i32_e32 vcc, v5, v6
	v_lshlrev_b32_e32 v3, 3, v0
	s_add_u32 s0, s8, 0x18000000
	v_cndmask_b32_e32 v5, v4, v5, vcc
	v_lshlrev_b32_e32 v161, 2, v5
	v_xor_b32_e32 v5, 2, v4
	v_and_b32_e32 v2, 0x78, v3
	s_addc_u32 s1, s9, 0
	v_cmp_lt_i32_e32 vcc, v5, v6
	s_add_i32 s10, 0, 0x10000
	v_lshlrev_b32_e32 v6, 1, v0
	v_cndmask_b32_e32 v4, v4, v5, vcc
	v_lshlrev_b32_e32 v146, 2, v2
	v_and_b32_e32 v5, 0xc0, v254
	v_and_b32_e32 v6, 32, v6
	v_and_b32_e32 v3, 0x118, v3
	s_cmp_lg_u32 0, -1
	v_cmp_eq_u32_e64 s[4:5], 0, v154
	v_lshl_add_u64 v[154:155], s[2:3], 0, v[146:147]
	v_or3_b32 v3, v6, v5, v3
	s_cselect_b32 s2, 0, 0
	v_add_u32_e32 v186, s2, v3
	v_readlane_b32 s2, v255, 12
	s_lshl_b32 s2, s2, 5
	v_and_or_b32 v1, v156, 3, v1
	v_lshlrev_b32_e32 v3, 2, v0
	s_and_b32 s3, s2, 0x60
	v_lshlrev_b32_e32 v1, 6, v1
	v_and_b32_e32 v3, 60, v3
	v_readlane_b32 s15, v255, 0
	v_add3_u32 v3, 0, v1, v3
	s_cmpk_gt_u32 s15, 0xff
	v_lshlrev_b32_e32 v1, 1, v156
	v_lshl_add_u32 v185, v211, 3, s10
	v_lshl_add_u32 v187, v156, 3, s10
	s_cselect_b64 s[12:13], -1, 0
	v_and_b32_e32 v1, 8, v1
	s_and_b32 s10, s15, 0xffffff00
	v_lshlrev_b32_e32 v184, 2, v4
	v_lshlrev_b32_e32 v150, 12, v156
	v_or_b32_e32 v4, 32, v156
	v_and_or_b32 v5, v156, 16, v1
	v_lshl_or_b32 v156, v160, 3, s10
	v_readlane_b32 s10, v255, 3
	s_and_b32 s2, s2, 0x7fffff80
	v_lshl_or_b32 v188, v158, 2, s3
	s_lshl_b32 s3, s96, 6
	s_lshl_b32 s14, s10, 6
	s_bitcmp1_b32 s96, 0
	v_and_or_b32 v1, v4, 48, v1
	s_cselect_b64 s[16:17], -1, 0
	s_bitcmp1_b32 s10, 0
	v_lshlrev_b32_e32 v152, 12, v4
	v_lshlrev_b32_e32 v4, 8, v1
	s_cselect_b64 s[18:19], -1, 0
	v_lshl_or_b32 v158, v160, 2, s2
	v_and_b32_e32 v1, 32, v0
	s_lshl_b32 s2, s15, 7
	v_lshlrev_b32_e32 v5, 8, v5
	v_lshrrev_b32_e32 v1, 1, v1
	v_lshlrev_b32_e32 v6, 8, v160
	s_and_b32 s2, s2, 0x6000
	v_lshlrev_b32_e32 v146, 2, v188
	s_mov_b32 s11, 0
	v_mov_b32_e32 v151, v147
	v_mov_b32_e32 v153, v147
	v_mov_b32_e32 v157, v147
	v_or_b32_e32 v189, 8, v188
	v_or_b32_e32 v190, 16, v188
	v_or_b32_e32 v191, 24, v188
	v_mov_b32_e32 v159, v147
	v_or3_b32 v160, s2, v6, v1
	v_mov_b32_e32 v1, v147
	v_lshl_add_u64 v[162:163], s[6:7], 0, v[146:147]
	s_mov_b32 s20, 0x3a000000
	s_mov_b32 s15, 0xf800000
	v_mov_b32_e32 v192, 0x260
	v_lshlrev_b32_e32 v146, 1, v2
	s_mov_b32 s21, 0x1000000
	v_add_u32_e32 v193, v3, v5
	v_add_u32_e32 v194, v3, v4
	s_mov_b32 s33, 0x14001000
	s_mov_b32 s34, 0x14003000
	s_brev_b32 s36, 12
	s_mov_b32 s37, 0x30001000
	s_mov_b64 s[22:23], 0x200
	s_mov_b64 s[24:25], 0x100
	s_mov_b64 s[26:27], 0x8000
	s_mov_b32 s38, s96
	s_branch .LBB0_720

	.amdhsa_kernel _Z10fwd_kernel4Args
		.amdhsa_group_segment_fixed_size 0
		.amdhsa_private_segment_fixed_size 0
		.amdhsa_kernarg_size 464
		.amdhsa_user_sgpr_count 2
		.amdhsa_user_sgpr_dispatch_ptr 0
		.amdhsa_user_sgpr_queue_ptr 0
		.amdhsa_user_sgpr_kernarg_segment_ptr 1
		.amdhsa_user_sgpr_dispatch_id 0
		.amdhsa_user_sgpr_kernarg_preload_length 0
		.amdhsa_user_sgpr_kernarg_preload_offset 0
		.amdhsa_user_sgpr_private_segment_size 0
		.amdhsa_uses_dynamic_stack 0
		.amdhsa_enable_private_segment 0
		.amdhsa_system_sgpr_workgroup_id_x 1
		.amdhsa_system_sgpr_workgroup_id_y 0
		.amdhsa_system_sgpr_workgroup_id_z 0
		.amdhsa_system_sgpr_workgroup_info 0
		.amdhsa_system_vgpr_workitem_id 0
		.amdhsa_next_free_vgpr 256
		.amdhsa_next_free_sgpr 102
		.amdhsa_accum_offset 256
		.amdhsa_reserve_vcc 1
		.amdhsa_float_round_mode_32 0
		.amdhsa_float_round_mode_16_64 0
		.amdhsa_float_denorm_mode_32 3
		.amdhsa_float_denorm_mode_16_64 3
		.amdhsa_dx10_clamp 1
		.amdhsa_ieee_mode 1
		.amdhsa_fp16_overflow 0
		.amdhsa_tg_split 0
		.amdhsa_exception_fp_ieee_invalid_op 0
		.amdhsa_exception_fp_denorm_src 0
		.amdhsa_exception_fp_ieee_div_zero 0
		.amdhsa_exception_fp_ieee_overflow 0
		.amdhsa_exception_fp_ieee_underflow 0
		.amdhsa_exception_fp_ieee_inexact 0
		.amdhsa_exception_int_div_zero 0
	.end_amdhsa_kernel

amdhsa.kernels:
  - .agpr_count:     0
    .args:
      - .offset:         0
        .size:           208
        .value_kind:     by_value
      - .offset:         208
        .size:           4
        .value_kind:     hidden_block_count_x
      - .offset:         212
        .size:           4
        .value_kind:     hidden_block_count_y
      - .offset:         216
        .size:           4
        .value_kind:     hidden_block_count_z
      - .offset:         220
        .size:           2
        .value_kind:     hidden_group_size_x
      - .offset:         222
        .size:           2
        .value_kind:     hidden_group_size_y
      - .offset:         224
        .size:           2
        .value_kind:     hidden_group_size_z
      - .offset:         226
        .size:           2
        .value_kind:     hidden_remainder_x
      - .offset:         228
        .size:           2
        .value_kind:     hidden_remainder_y
      - .offset:         230
        .size:           2
        .value_kind:     hidden_remainder_z
      - .offset:         248
        .size:           8
        .value_kind:     hidden_global_offset_x
      - .offset:         256
        .size:           8
        .value_kind:     hidden_global_offset_y
      - .offset:         264
        .size:           8
        .value_kind:     hidden_global_offset_z
      - .offset:         272
        .size:           2
        .value_kind:     hidden_grid_dims
      - .offset:         328
        .size:           4
        .value_kind:     hidden_dynamic_lds_size
    .group_segment_fixed_size: 0
    .kernarg_segment_align: 8
    .kernarg_segment_size: 464
    .language:       OpenCL C
    .language_version:
      - 2
      - 0
    .max_flat_workgroup_size: 512
    .name:           _Z10fwd_kernel4Args
    .private_segment_fixed_size: 0
    .sgpr_count:     108
    .sgpr_spill_count: 37
    .symbol:         _Z10fwd_kernel4Args.kd
    .uniform_work_group_size: 1
    .uses_dynamic_stack: false
    .vgpr_count:     256
    .vgpr_spill_count: 0
    .wavefront_size: 64
